# idx histogram scans rewritten: 4 rows per wave processed together, DPP suffix scan + in-register bin search (no serialized LDS round trips)
# speedup vs baseline: 1.0051x; 1.0051x over previous
; DI void idx_scan(const u32* hq, int need, u32* outbin, u32* outneed, int q, int lane) {
;   u32 c = 0;
; #pragma unroll
;   for (int w = 0; w < 8; ++w) { u32 v = hq[8 * lane + w]; c += (v & 0xffffu) + (v >> 16); }
;   u32 incl = c;
; #pragma unroll
;   for (int o = 1; o < 64; o <<= 1) { u32 v = __shfl_down(incl, o); if (lane + o < 64) incl += v; }
;   const u32 above = incl - c;
;   if ((int)above < need && need <= (int)incl) {
; DI void idx_job(const Params& p, int b, int qg, unsigned char* smem) {
;     ...
;   for (int qq = 0; qq < 4; ++qq) idx_scan(hist + (wave * 4 + qq) * 512, 256, binA, needB, wave * 4 + qq, lane);
.LBB0_409:
	s_or_b64 exec, exec, s[2:3]
	s_waitcnt vmcnt(1)
	v_and_b32_e32 v43, 63, v207
	v_cmp_ne_u32_e64 s[4:5], 63, v43
	v_lshl_add_u32 v140, v109, 13, v96
	v_lshl_add_u32 v139, v141, 5, v140
	v_addc_co_u32_e64 v44, s[4:5], 0, v207, s[4:5]
	s_waitcnt lgkmcnt(0)
	s_barrier
	s_waitcnt vmcnt(0)
	v_lshl_add_u32 v46, v109, 13, v96
	v_and_b32_e32 v48, 63, v207
	v_lshl_add_u32 v47, v109, 4, v96
	v_lshl_add_u32 v46, v48, 5, v46
	v_add_u32_e32 v47, 0xc000, v47
	ds_read_b128 v[168:171], v46
	ds_read_b128 v[172:175], v46 offset:16
	ds_read_b128 v[176:179], v46 offset:2048
	ds_read_b128 v[180:183], v46 offset:2064
	ds_read_b128 v[184:187], v46 offset:4096
	ds_read_b128 v[188:191], v46 offset:4112
	ds_read_b128 v[226:229], v46 offset:6144
	ds_read_b128 v[230:233], v46 offset:6160
	v_mov_b32_e32 v238, 0x100
	v_mov_b32_e32 v239, 0x100
	v_mov_b32_e32 v240, 0x100
	v_mov_b32_e32 v241, 0x100
	s_waitcnt lgkmcnt(0)
	v_add3_u32 v192, v168, v169, v170
	v_add3_u32 v193, v176, v177, v178
	v_add3_u32 v194, v184, v185, v186
	v_add3_u32 v195, v226, v227, v228
	v_add3_u32 v192, v192, v171, v172
	v_add3_u32 v193, v193, v179, v180
	v_add3_u32 v194, v194, v187, v188
	v_add3_u32 v195, v195, v229, v230
	v_add3_u32 v192, v192, v173, v174
	v_add3_u32 v193, v193, v181, v182
	v_add3_u32 v194, v194, v189, v190
	v_add3_u32 v195, v195, v231, v232
	v_add_u32_e32 v192, v192, v175
	v_add_u32_e32 v193, v193, v183
	v_add_u32_e32 v194, v194, v191
	v_add_u32_e32 v195, v195, v233
	v_add_u32_sdwa v192, v192, v192 dst_sel:DWORD dst_unused:UNUSED_PAD src0_sel:WORD_0 src1_sel:WORD_1
	v_add_u32_sdwa v193, v193, v193 dst_sel:DWORD dst_unused:UNUSED_PAD src0_sel:WORD_0 src1_sel:WORD_1
	v_add_u32_sdwa v194, v194, v194 dst_sel:DWORD dst_unused:UNUSED_PAD src0_sel:WORD_0 src1_sel:WORD_1
	v_add_u32_sdwa v195, v195, v195 dst_sel:DWORD dst_unused:UNUSED_PAD src0_sel:WORD_0 src1_sel:WORD_1
	v_mov_b32_e32 v234, v192
	v_mov_b32_e32 v235, v193
	v_mov_b32_e32 v236, v194
	v_mov_b32_e32 v237, v195
	v_add_u32_dpp v234, v234, v234 row_shl:1 row_mask:0xf bank_mask:0xf
	v_add_u32_dpp v235, v235, v235 row_shl:1 row_mask:0xf bank_mask:0xf
	v_add_u32_dpp v236, v236, v236 row_shl:1 row_mask:0xf bank_mask:0xf
	v_add_u32_dpp v237, v237, v237 row_shl:1 row_mask:0xf bank_mask:0xf
	v_add_u32_dpp v234, v234, v234 row_shl:2 row_mask:0xf bank_mask:0xf
	v_add_u32_dpp v235, v235, v235 row_shl:2 row_mask:0xf bank_mask:0xf
	v_add_u32_dpp v236, v236, v236 row_shl:2 row_mask:0xf bank_mask:0xf
	v_add_u32_dpp v237, v237, v237 row_shl:2 row_mask:0xf bank_mask:0xf
	v_add_u32_dpp v234, v234, v234 row_shl:4 row_mask:0xf bank_mask:0xf
	v_add_u32_dpp v235, v235, v235 row_shl:4 row_mask:0xf bank_mask:0xf
	v_add_u32_dpp v236, v236, v236 row_shl:4 row_mask:0xf bank_mask:0xf
	v_add_u32_dpp v237, v237, v237 row_shl:4 row_mask:0xf bank_mask:0xf
	v_add_u32_dpp v234, v234, v234 row_shl:8 row_mask:0xf bank_mask:0xf
	v_add_u32_dpp v235, v235, v235 row_shl:8 row_mask:0xf bank_mask:0xf
	v_add_u32_dpp v236, v236, v236 row_shl:8 row_mask:0xf bank_mask:0xf
	v_add_u32_dpp v237, v237, v237 row_shl:8 row_mask:0xf bank_mask:0xf
	s_nop 1
	v_readlane_b32 s40, v234, 16
	v_readlane_b32 s41, v234, 32
	v_readlane_b32 s42, v234, 48
	v_readlane_b32 s43, v235, 16
	v_readlane_b32 s44, v235, 32
	v_readlane_b32 s45, v235, 48
	v_readlane_b32 s46, v236, 16
	v_readlane_b32 s47, v236, 32
	v_readlane_b32 s48, v236, 48
	v_readlane_b32 s49, v237, 16
	v_readlane_b32 s50, v237, 32
	v_readlane_b32 s51, v237, 48
	s_nop 0
	s_add_i32 s41, s41, s42
	s_add_i32 s40, s40, s41
	s_add_i32 s44, s44, s45
	s_add_i32 s43, s43, s44
	s_add_i32 s47, s47, s48
	s_add_i32 s46, s46, s47
	s_add_i32 s50, s50, s51
	s_add_i32 s49, s49, s50
	s_mov_b32 exec_lo, 0xffff
	s_mov_b32 exec_hi, 0
	v_add_u32_e32 v234, s40, v234
	v_add_u32_e32 v235, s43, v235
	v_add_u32_e32 v236, s46, v236
	v_add_u32_e32 v237, s49, v237
	s_mov_b32 exec_lo, 0xffff0000
	v_add_u32_e32 v234, s41, v234
	v_add_u32_e32 v235, s44, v235
	v_add_u32_e32 v236, s47, v236
	v_add_u32_e32 v237, s50, v237
	s_mov_b32 exec_lo, 0
	s_mov_b32 exec_hi, 0xffff
	v_add_u32_e32 v234, s42, v234
	v_add_u32_e32 v235, s45, v235
	v_add_u32_e32 v236, s48, v236
	v_add_u32_e32 v237, s51, v237
	s_mov_b64 exec, -1
	v_sub_u32_e32 v158, v234, v192
	v_sub_u32_e32 v159, v235, v193
	v_sub_u32_e32 v160, v236, v194
	v_sub_u32_e32 v161, v237, v195
	v_cmp_lt_u32_e64 s[4:5], v158, v238
	v_cmp_lt_u32_e64 s[6:7], v159, v239
	v_cmp_lt_u32_e64 s[8:9], v160, v240
	v_cmp_lt_u32_e64 s[28:29], v161, v241
	v_cmp_le_u32_e64 s[40:41], v238, v234
	v_cmp_le_u32_e64 s[42:43], v239, v235
	v_cmp_le_u32_e64 s[44:45], v240, v236
	v_cmp_le_u32_e64 s[46:47], v241, v237
	v_mov_b32_e32 v42, v158
	v_mov_b32_e32 v43, v159
	v_mov_b32_e32 v44, v160
	v_mov_b32_e32 v45, v161
	v_mov_b32_e32 v162, 15
	v_mov_b32_e32 v163, 15
	v_mov_b32_e32 v164, 15
	v_mov_b32_e32 v165, 15
	s_and_b64 s[40:41], s[40:41], s[4:5]
	s_and_b64 s[42:43], s[42:43], s[6:7]
	s_and_b64 s[44:45], s[44:45], s[8:9]
	s_and_b64 s[46:47], s[46:47], s[28:29]
	v_add_u32_sdwa v158, v175, v158 dst_sel:DWORD dst_unused:UNUSED_PAD src0_sel:WORD_1 src1_sel:DWORD
	v_add_u32_sdwa v159, v183, v159 dst_sel:DWORD dst_unused:UNUSED_PAD src0_sel:WORD_1 src1_sel:DWORD
	v_add_u32_sdwa v160, v191, v160 dst_sel:DWORD dst_unused:UNUSED_PAD src0_sel:WORD_1 src1_sel:DWORD
	v_add_u32_sdwa v161, v233, v161 dst_sel:DWORD dst_unused:UNUSED_PAD src0_sel:WORD_1 src1_sel:DWORD
	v_cmp_lt_u32_e64 s[4:5], v158, v238
	v_cmp_lt_u32_e64 s[6:7], v159, v239
	v_cmp_lt_u32_e64 s[8:9], v160, v240
	v_cmp_lt_u32_e64 s[28:29], v161, v241
	v_cndmask_b32_e64 v42, v42, v158, s[4:5]
	v_cndmask_b32_e64 v162, v162, 14, s[4:5]
	v_cndmask_b32_e64 v43, v43, v159, s[6:7]
; DI void idx_scan(const u32* hq, int need, u32* outbin, u32* outneed, int q, int lane) {
;     ...
;   if ((int)above < need && need <= (int)incl) {
;     u32 cum = above;
;     ...
;       u32 cnt = (hq[bin >> 1] >> ((bin & 1) * 16)) & 0xffffu;
;       if ((int)(cum + cnt) >= need) { outbin[q] = (u32)bin; outneed[q] = (u32)need - cum; break; }
;       cum += cnt;
;     }
	v_cndmask_b32_e64 v163, v163, 14, s[6:7]
	v_cndmask_b32_e64 v44, v44, v160, s[8:9]
	v_cndmask_b32_e64 v164, v164, 14, s[8:9]
	v_cndmask_b32_e64 v45, v45, v161, s[28:29]
	v_cndmask_b32_e64 v165, v165, 14, s[28:29]
	v_add_u32_sdwa v158, v175, v158 dst_sel:DWORD dst_unused:UNUSED_PAD src0_sel:WORD_0 src1_sel:DWORD
	v_add_u32_sdwa v159, v183, v159 dst_sel:DWORD dst_unused:UNUSED_PAD src0_sel:WORD_0 src1_sel:DWORD
	v_add_u32_sdwa v160, v191, v160 dst_sel:DWORD dst_unused:UNUSED_PAD src0_sel:WORD_0 src1_sel:DWORD
	v_add_u32_sdwa v161, v233, v161 dst_sel:DWORD dst_unused:UNUSED_PAD src0_sel:WORD_0 src1_sel:DWORD
	v_cmp_lt_u32_e64 s[4:5], v158, v238
	v_cmp_lt_u32_e64 s[6:7], v159, v239
	v_cmp_lt_u32_e64 s[8:9], v160, v240
	v_cmp_lt_u32_e64 s[28:29], v161, v241
	v_cndmask_b32_e64 v42, v42, v158, s[4:5]
	v_cndmask_b32_e64 v162, v162, 13, s[4:5]
	v_cndmask_b32_e64 v43, v43, v159, s[6:7]
	v_cndmask_b32_e64 v163, v163, 13, s[6:7]
	v_cndmask_b32_e64 v44, v44, v160, s[8:9]
	v_cndmask_b32_e64 v164, v164, 13, s[8:9]
	v_cndmask_b32_e64 v45, v45, v161, s[28:29]
	v_cndmask_b32_e64 v165, v165, 13, s[28:29]
	v_add_u32_sdwa v158, v174, v158 dst_sel:DWORD dst_unused:UNUSED_PAD src0_sel:WORD_1 src1_sel:DWORD
	v_add_u32_sdwa v159, v182, v159 dst_sel:DWORD dst_unused:UNUSED_PAD src0_sel:WORD_1 src1_sel:DWORD
	v_add_u32_sdwa v160, v190, v160 dst_sel:DWORD dst_unused:UNUSED_PAD src0_sel:WORD_1 src1_sel:DWORD
	v_add_u32_sdwa v161, v232, v161 dst_sel:DWORD dst_unused:UNUSED_PAD src0_sel:WORD_1 src1_sel:DWORD
	v_cmp_lt_u32_e64 s[4:5], v158, v238
	v_cmp_lt_u32_e64 s[6:7], v159, v239
	v_cmp_lt_u32_e64 s[8:9], v160, v240
	v_cmp_lt_u32_e64 s[28:29], v161, v241
	v_cndmask_b32_e64 v42, v42, v158, s[4:5]
	v_cndmask_b32_e64 v162, v162, 12, s[4:5]
	v_cndmask_b32_e64 v43, v43, v159, s[6:7]
	v_cndmask_b32_e64 v163, v163, 12, s[6:7]
	v_cndmask_b32_e64 v44, v44, v160, s[8:9]
	v_cndmask_b32_e64 v164, v164, 12, s[8:9]
	v_cndmask_b32_e64 v45, v45, v161, s[28:29]
	v_cndmask_b32_e64 v165, v165, 12, s[28:29]
	v_add_u32_sdwa v158, v174, v158 dst_sel:DWORD dst_unused:UNUSED_PAD src0_sel:WORD_0 src1_sel:DWORD
	v_add_u32_sdwa v159, v182, v159 dst_sel:DWORD dst_unused:UNUSED_PAD src0_sel:WORD_0 src1_sel:DWORD
	v_add_u32_sdwa v160, v190, v160 dst_sel:DWORD dst_unused:UNUSED_PAD src0_sel:WORD_0 src1_sel:DWORD
	v_add_u32_sdwa v161, v232, v161 dst_sel:DWORD dst_unused:UNUSED_PAD src0_sel:WORD_0 src1_sel:DWORD
	v_cmp_lt_u32_e64 s[4:5], v158, v238
	v_cmp_lt_u32_e64 s[6:7], v159, v239
	v_cmp_lt_u32_e64 s[8:9], v160, v240
	v_cmp_lt_u32_e64 s[28:29], v161, v241
	v_cndmask_b32_e64 v42, v42, v158, s[4:5]
	v_cndmask_b32_e64 v162, v162, 11, s[4:5]
	v_cndmask_b32_e64 v43, v43, v159, s[6:7]
	v_cndmask_b32_e64 v163, v163, 11, s[6:7]
	v_cndmask_b32_e64 v44, v44, v160, s[8:9]
	v_cndmask_b32_e64 v164, v164, 11, s[8:9]
	v_cndmask_b32_e64 v45, v45, v161, s[28:29]
	v_cndmask_b32_e64 v165, v165, 11, s[28:29]
	v_add_u32_sdwa v158, v173, v158 dst_sel:DWORD dst_unused:UNUSED_PAD src0_sel:WORD_1 src1_sel:DWORD
	v_add_u32_sdwa v159, v181, v159 dst_sel:DWORD dst_unused:UNUSED_PAD src0_sel:WORD_1 src1_sel:DWORD
	v_add_u32_sdwa v160, v189, v160 dst_sel:DWORD dst_unused:UNUSED_PAD src0_sel:WORD_1 src1_sel:DWORD
	v_add_u32_sdwa v161, v231, v161 dst_sel:DWORD dst_unused:UNUSED_PAD src0_sel:WORD_1 src1_sel:DWORD
	v_cmp_lt_u32_e64 s[4:5], v158, v238
	v_cmp_lt_u32_e64 s[6:7], v159, v239
	v_cmp_lt_u32_e64 s[8:9], v160, v240
	v_cmp_lt_u32_e64 s[28:29], v161, v241
	v_cndmask_b32_e64 v42, v42, v158, s[4:5]
	v_cndmask_b32_e64 v162, v162, 10, s[4:5]
	v_cndmask_b32_e64 v43, v43, v159, s[6:7]
	v_cndmask_b32_e64 v163, v163, 10, s[6:7]
	v_cndmask_b32_e64 v44, v44, v160, s[8:9]
	v_cndmask_b32_e64 v164, v164, 10, s[8:9]
	v_cndmask_b32_e64 v45, v45, v161, s[28:29]
	v_cndmask_b32_e64 v165, v165, 10, s[28:29]
	v_add_u32_sdwa v158, v173, v158 dst_sel:DWORD dst_unused:UNUSED_PAD src0_sel:WORD_0 src1_sel:DWORD
	v_add_u32_sdwa v159, v181, v159 dst_sel:DWORD dst_unused:UNUSED_PAD src0_sel:WORD_0 src1_sel:DWORD
	v_add_u32_sdwa v160, v189, v160 dst_sel:DWORD dst_unused:UNUSED_PAD src0_sel:WORD_0 src1_sel:DWORD
	v_add_u32_sdwa v161, v231, v161 dst_sel:DWORD dst_unused:UNUSED_PAD src0_sel:WORD_0 src1_sel:DWORD
	v_cmp_lt_u32_e64 s[4:5], v158, v238
	v_cmp_lt_u32_e64 s[6:7], v159, v239
	v_cmp_lt_u32_e64 s[8:9], v160, v240
	v_cmp_lt_u32_e64 s[28:29], v161, v241
	v_cndmask_b32_e64 v42, v42, v158, s[4:5]
	v_cndmask_b32_e64 v162, v162, 9, s[4:5]
	v_cndmask_b32_e64 v43, v43, v159, s[6:7]
	v_cndmask_b32_e64 v163, v163, 9, s[6:7]
	v_cndmask_b32_e64 v44, v44, v160, s[8:9]
	v_cndmask_b32_e64 v164, v164, 9, s[8:9]
	v_cndmask_b32_e64 v45, v45, v161, s[28:29]
	v_cndmask_b32_e64 v165, v165, 9, s[28:29]
	v_add_u32_sdwa v158, v172, v158 dst_sel:DWORD dst_unused:UNUSED_PAD src0_sel:WORD_1 src1_sel:DWORD
	v_add_u32_sdwa v159, v180, v159 dst_sel:DWORD dst_unused:UNUSED_PAD src0_sel:WORD_1 src1_sel:DWORD
	v_add_u32_sdwa v160, v188, v160 dst_sel:DWORD dst_unused:UNUSED_PAD src0_sel:WORD_1 src1_sel:DWORD
	v_add_u32_sdwa v161, v230, v161 dst_sel:DWORD dst_unused:UNUSED_PAD src0_sel:WORD_1 src1_sel:DWORD
	v_cmp_lt_u32_e64 s[4:5], v158, v238
	v_cmp_lt_u32_e64 s[6:7], v159, v239
	v_cmp_lt_u32_e64 s[8:9], v160, v240
	v_cmp_lt_u32_e64 s[28:29], v161, v241
	v_cndmask_b32_e64 v42, v42, v158, s[4:5]
	v_cndmask_b32_e64 v162, v162, 8, s[4:5]
	v_cndmask_b32_e64 v43, v43, v159, s[6:7]
	v_cndmask_b32_e64 v163, v163, 8, s[6:7]
	v_cndmask_b32_e64 v44, v44, v160, s[8:9]
	v_cndmask_b32_e64 v164, v164, 8, s[8:9]
	v_cndmask_b32_e64 v45, v45, v161, s[28:29]
	v_cndmask_b32_e64 v165, v165, 8, s[28:29]
	v_add_u32_sdwa v158, v172, v158 dst_sel:DWORD dst_unused:UNUSED_PAD src0_sel:WORD_0 src1_sel:DWORD
; DI void idx_scan(const u32* hq, int need, u32* outbin, u32* outneed, int q, int lane) {
;     ...
;   if ((int)above < need && need <= (int)incl) {
;     u32 cum = above;
;     ...
;       u32 cnt = (hq[bin >> 1] >> ((bin & 1) * 16)) & 0xffffu;
;       if ((int)(cum + cnt) >= need) { outbin[q] = (u32)bin; outneed[q] = (u32)need - cum; break; }
;       cum += cnt;
;     }
	v_add_u32_sdwa v159, v180, v159 dst_sel:DWORD dst_unused:UNUSED_PAD src0_sel:WORD_0 src1_sel:DWORD
	v_add_u32_sdwa v160, v188, v160 dst_sel:DWORD dst_unused:UNUSED_PAD src0_sel:WORD_0 src1_sel:DWORD
	v_add_u32_sdwa v161, v230, v161 dst_sel:DWORD dst_unused:UNUSED_PAD src0_sel:WORD_0 src1_sel:DWORD
	v_cmp_lt_u32_e64 s[4:5], v158, v238
	v_cmp_lt_u32_e64 s[6:7], v159, v239
	v_cmp_lt_u32_e64 s[8:9], v160, v240
	v_cmp_lt_u32_e64 s[28:29], v161, v241
	v_cndmask_b32_e64 v42, v42, v158, s[4:5]
	v_cndmask_b32_e64 v162, v162, 7, s[4:5]
	v_cndmask_b32_e64 v43, v43, v159, s[6:7]
	v_cndmask_b32_e64 v163, v163, 7, s[6:7]
	v_cndmask_b32_e64 v44, v44, v160, s[8:9]
	v_cndmask_b32_e64 v164, v164, 7, s[8:9]
	v_cndmask_b32_e64 v45, v45, v161, s[28:29]
	v_cndmask_b32_e64 v165, v165, 7, s[28:29]
	v_add_u32_sdwa v158, v171, v158 dst_sel:DWORD dst_unused:UNUSED_PAD src0_sel:WORD_1 src1_sel:DWORD
	v_add_u32_sdwa v159, v179, v159 dst_sel:DWORD dst_unused:UNUSED_PAD src0_sel:WORD_1 src1_sel:DWORD
	v_add_u32_sdwa v160, v187, v160 dst_sel:DWORD dst_unused:UNUSED_PAD src0_sel:WORD_1 src1_sel:DWORD
	v_add_u32_sdwa v161, v229, v161 dst_sel:DWORD dst_unused:UNUSED_PAD src0_sel:WORD_1 src1_sel:DWORD
	v_cmp_lt_u32_e64 s[4:5], v158, v238
	v_cmp_lt_u32_e64 s[6:7], v159, v239
	v_cmp_lt_u32_e64 s[8:9], v160, v240
	v_cmp_lt_u32_e64 s[28:29], v161, v241
	v_cndmask_b32_e64 v42, v42, v158, s[4:5]
	v_cndmask_b32_e64 v162, v162, 6, s[4:5]
	v_cndmask_b32_e64 v43, v43, v159, s[6:7]
	v_cndmask_b32_e64 v163, v163, 6, s[6:7]
	v_cndmask_b32_e64 v44, v44, v160, s[8:9]
	v_cndmask_b32_e64 v164, v164, 6, s[8:9]
	v_cndmask_b32_e64 v45, v45, v161, s[28:29]
	v_cndmask_b32_e64 v165, v165, 6, s[28:29]
	v_add_u32_sdwa v158, v171, v158 dst_sel:DWORD dst_unused:UNUSED_PAD src0_sel:WORD_0 src1_sel:DWORD
	v_add_u32_sdwa v159, v179, v159 dst_sel:DWORD dst_unused:UNUSED_PAD src0_sel:WORD_0 src1_sel:DWORD
	v_add_u32_sdwa v160, v187, v160 dst_sel:DWORD dst_unused:UNUSED_PAD src0_sel:WORD_0 src1_sel:DWORD
	v_add_u32_sdwa v161, v229, v161 dst_sel:DWORD dst_unused:UNUSED_PAD src0_sel:WORD_0 src1_sel:DWORD
	v_cmp_lt_u32_e64 s[4:5], v158, v238
	v_cmp_lt_u32_e64 s[6:7], v159, v239
	v_cmp_lt_u32_e64 s[8:9], v160, v240
	v_cmp_lt_u32_e64 s[28:29], v161, v241
	v_cndmask_b32_e64 v42, v42, v158, s[4:5]
	v_cndmask_b32_e64 v162, v162, 5, s[4:5]
	v_cndmask_b32_e64 v43, v43, v159, s[6:7]
	v_cndmask_b32_e64 v163, v163, 5, s[6:7]
	v_cndmask_b32_e64 v44, v44, v160, s[8:9]
	v_cndmask_b32_e64 v164, v164, 5, s[8:9]
	v_cndmask_b32_e64 v45, v45, v161, s[28:29]
	v_cndmask_b32_e64 v165, v165, 5, s[28:29]
	v_add_u32_sdwa v158, v170, v158 dst_sel:DWORD dst_unused:UNUSED_PAD src0_sel:WORD_1 src1_sel:DWORD
	v_add_u32_sdwa v159, v178, v159 dst_sel:DWORD dst_unused:UNUSED_PAD src0_sel:WORD_1 src1_sel:DWORD
	v_add_u32_sdwa v160, v186, v160 dst_sel:DWORD dst_unused:UNUSED_PAD src0_sel:WORD_1 src1_sel:DWORD
	v_add_u32_sdwa v161, v228, v161 dst_sel:DWORD dst_unused:UNUSED_PAD src0_sel:WORD_1 src1_sel:DWORD
	v_cmp_lt_u32_e64 s[4:5], v158, v238
	v_cmp_lt_u32_e64 s[6:7], v159, v239
	v_cmp_lt_u32_e64 s[8:9], v160, v240
	v_cmp_lt_u32_e64 s[28:29], v161, v241
	v_cndmask_b32_e64 v42, v42, v158, s[4:5]
	v_cndmask_b32_e64 v162, v162, 4, s[4:5]
	v_cndmask_b32_e64 v43, v43, v159, s[6:7]
	v_cndmask_b32_e64 v163, v163, 4, s[6:7]
	v_cndmask_b32_e64 v44, v44, v160, s[8:9]
	v_cndmask_b32_e64 v164, v164, 4, s[8:9]
	v_cndmask_b32_e64 v45, v45, v161, s[28:29]
	v_cndmask_b32_e64 v165, v165, 4, s[28:29]
	v_add_u32_sdwa v158, v170, v158 dst_sel:DWORD dst_unused:UNUSED_PAD src0_sel:WORD_0 src1_sel:DWORD
	v_add_u32_sdwa v159, v178, v159 dst_sel:DWORD dst_unused:UNUSED_PAD src0_sel:WORD_0 src1_sel:DWORD
	v_add_u32_sdwa v160, v186, v160 dst_sel:DWORD dst_unused:UNUSED_PAD src0_sel:WORD_0 src1_sel:DWORD
	v_add_u32_sdwa v161, v228, v161 dst_sel:DWORD dst_unused:UNUSED_PAD src0_sel:WORD_0 src1_sel:DWORD
	v_cmp_lt_u32_e64 s[4:5], v158, v238
	v_cmp_lt_u32_e64 s[6:7], v159, v239
	v_cmp_lt_u32_e64 s[8:9], v160, v240
	v_cmp_lt_u32_e64 s[28:29], v161, v241
	v_cndmask_b32_e64 v42, v42, v158, s[4:5]
	v_cndmask_b32_e64 v162, v162, 3, s[4:5]
	v_cndmask_b32_e64 v43, v43, v159, s[6:7]
	v_cndmask_b32_e64 v163, v163, 3, s[6:7]
	v_cndmask_b32_e64 v44, v44, v160, s[8:9]
	v_cndmask_b32_e64 v164, v164, 3, s[8:9]
	v_cndmask_b32_e64 v45, v45, v161, s[28:29]
	v_cndmask_b32_e64 v165, v165, 3, s[28:29]
; DI void idx_scan(const u32* hq, int need, u32* outbin, u32* outneed, int q, int lane) {
;     ...
;   if ((int)above < need && need <= (int)incl) {
;     u32 cum = above;
;     ...
;       u32 cnt = (hq[bin >> 1] >> ((bin & 1) * 16)) & 0xffffu;
;       if ((int)(cum + cnt) >= need) { outbin[q] = (u32)bin; outneed[q] = (u32)need - cum; break; }
;       cum += cnt;
;     }
;   }
; DI void idx_job(const Params& p, int b, int qg, unsigned char* smem) {
;     ...
;   __syncthreads();
;   for (int i = tid; i < 8192; i += 256) hist[i] = 0u;
	v_add_u32_sdwa v158, v169, v158 dst_sel:DWORD dst_unused:UNUSED_PAD src0_sel:WORD_1 src1_sel:DWORD
	v_add_u32_sdwa v159, v177, v159 dst_sel:DWORD dst_unused:UNUSED_PAD src0_sel:WORD_1 src1_sel:DWORD
	v_add_u32_sdwa v160, v185, v160 dst_sel:DWORD dst_unused:UNUSED_PAD src0_sel:WORD_1 src1_sel:DWORD
	v_add_u32_sdwa v161, v227, v161 dst_sel:DWORD dst_unused:UNUSED_PAD src0_sel:WORD_1 src1_sel:DWORD
	v_cmp_lt_u32_e64 s[4:5], v158, v238
	v_cmp_lt_u32_e64 s[6:7], v159, v239
	v_cmp_lt_u32_e64 s[8:9], v160, v240
	v_cmp_lt_u32_e64 s[28:29], v161, v241
	v_cndmask_b32_e64 v42, v42, v158, s[4:5]
	v_cndmask_b32_e64 v162, v162, 2, s[4:5]
	v_cndmask_b32_e64 v43, v43, v159, s[6:7]
	v_cndmask_b32_e64 v163, v163, 2, s[6:7]
	v_cndmask_b32_e64 v44, v44, v160, s[8:9]
	v_cndmask_b32_e64 v164, v164, 2, s[8:9]
	v_cndmask_b32_e64 v45, v45, v161, s[28:29]
	v_cndmask_b32_e64 v165, v165, 2, s[28:29]
	v_add_u32_sdwa v158, v169, v158 dst_sel:DWORD dst_unused:UNUSED_PAD src0_sel:WORD_0 src1_sel:DWORD
	v_add_u32_sdwa v159, v177, v159 dst_sel:DWORD dst_unused:UNUSED_PAD src0_sel:WORD_0 src1_sel:DWORD
	v_add_u32_sdwa v160, v185, v160 dst_sel:DWORD dst_unused:UNUSED_PAD src0_sel:WORD_0 src1_sel:DWORD
	v_add_u32_sdwa v161, v227, v161 dst_sel:DWORD dst_unused:UNUSED_PAD src0_sel:WORD_0 src1_sel:DWORD
	v_cmp_lt_u32_e64 s[4:5], v158, v238
	v_cmp_lt_u32_e64 s[6:7], v159, v239
	v_cmp_lt_u32_e64 s[8:9], v160, v240
	v_cmp_lt_u32_e64 s[28:29], v161, v241
	v_cndmask_b32_e64 v42, v42, v158, s[4:5]
	v_cndmask_b32_e64 v162, v162, 1, s[4:5]
	v_cndmask_b32_e64 v43, v43, v159, s[6:7]
	v_cndmask_b32_e64 v163, v163, 1, s[6:7]
	v_cndmask_b32_e64 v44, v44, v160, s[8:9]
	v_cndmask_b32_e64 v164, v164, 1, s[8:9]
	v_cndmask_b32_e64 v45, v45, v161, s[28:29]
	v_cndmask_b32_e64 v165, v165, 1, s[28:29]
	v_add_u32_sdwa v158, v168, v158 dst_sel:DWORD dst_unused:UNUSED_PAD src0_sel:WORD_1 src1_sel:DWORD
	v_add_u32_sdwa v159, v176, v159 dst_sel:DWORD dst_unused:UNUSED_PAD src0_sel:WORD_1 src1_sel:DWORD
	v_add_u32_sdwa v160, v184, v160 dst_sel:DWORD dst_unused:UNUSED_PAD src0_sel:WORD_1 src1_sel:DWORD
	v_add_u32_sdwa v161, v226, v161 dst_sel:DWORD dst_unused:UNUSED_PAD src0_sel:WORD_1 src1_sel:DWORD
	v_cmp_lt_u32_e64 s[4:5], v158, v238
	v_cmp_lt_u32_e64 s[6:7], v159, v239
	v_cmp_lt_u32_e64 s[8:9], v160, v240
	v_cmp_lt_u32_e64 s[28:29], v161, v241
	v_cndmask_b32_e64 v42, v42, v158, s[4:5]
	v_cndmask_b32_e64 v162, v162, 0, s[4:5]
	v_cndmask_b32_e64 v43, v43, v159, s[6:7]
	v_cndmask_b32_e64 v163, v163, 0, s[6:7]
	v_cndmask_b32_e64 v44, v44, v160, s[8:9]
	v_cndmask_b32_e64 v164, v164, 0, s[8:9]
	v_cndmask_b32_e64 v45, v45, v161, s[28:29]
	v_cndmask_b32_e64 v165, v165, 0, s[28:29]
	v_add_u32_sdwa v158, v168, v158 dst_sel:DWORD dst_unused:UNUSED_PAD src0_sel:WORD_0 src1_sel:DWORD
	v_add_u32_sdwa v159, v176, v159 dst_sel:DWORD dst_unused:UNUSED_PAD src0_sel:WORD_0 src1_sel:DWORD
	v_add_u32_sdwa v160, v184, v160 dst_sel:DWORD dst_unused:UNUSED_PAD src0_sel:WORD_0 src1_sel:DWORD
	v_add_u32_sdwa v161, v226, v161 dst_sel:DWORD dst_unused:UNUSED_PAD src0_sel:WORD_0 src1_sel:DWORD
	v_cmp_lt_u32_e64 s[4:5], v158, v238
	v_cmp_lt_u32_e64 s[6:7], v159, v239
	v_cmp_lt_u32_e64 s[8:9], v160, v240
	v_cmp_lt_u32_e64 s[28:29], v161, v241
	v_cndmask_b32_e64 v42, v42, v158, s[4:5]
	v_cndmask_b32_e64 v162, v162, -1, s[4:5]
	v_cndmask_b32_e64 v43, v43, v159, s[6:7]
	v_cndmask_b32_e64 v163, v163, -1, s[6:7]
	v_cndmask_b32_e64 v44, v44, v160, s[8:9]
	v_cndmask_b32_e64 v164, v164, -1, s[8:9]
	v_cndmask_b32_e64 v45, v45, v161, s[28:29]
	v_cndmask_b32_e64 v165, v165, -1, s[28:29]
	v_lshl_add_u32 v50, v48, 4, v162
	v_lshl_add_u32 v51, v48, 4, v163
	v_lshl_add_u32 v52, v48, 4, v164
	v_lshl_add_u32 v53, v48, 4, v165
	v_sub_u32_e32 v54, v238, v42
	v_sub_u32_e32 v55, v239, v43
	v_sub_u32_e32 v242, v240, v44
	v_sub_u32_e32 v243, v241, v45
	s_mov_b64 exec, s[40:41]
	ds_write2_b32 v47, v50, v54 offset0:80 offset1:96
	s_mov_b64 exec, s[42:43]
	ds_write2_b32 v47, v51, v55 offset0:81 offset1:97
	s_mov_b64 exec, s[44:45]
	ds_write2_b32 v47, v52, v242 offset0:82 offset1:98
	s_mov_b64 exec, s[46:47]
	ds_write2_b32 v47, v53, v243 offset0:83 offset1:99
	s_mov_b64 exec, -1
	s_movk_i32 s2, 0x2000
	v_cmp_gt_i32_e64 s[4:5], s2, v86
	s_waitcnt lgkmcnt(0)
	s_barrier
	s_and_saveexec_b64 s[2:3], s[4:5]
	s_cbranch_execz .LBB0_602
	s_mov_b64 s[6:7], 0

; DI void idx_scan(const u32* hq, int need, u32* outbin, u32* outneed, int q, int lane) {
;   u32 c = 0;
; #pragma unroll
;   for (int w = 0; w < 8; ++w) { u32 v = hq[8 * lane + w]; c += (v & 0xffffu) + (v >> 16); }
;   u32 incl = c;
; #pragma unroll
;   for (int o = 1; o < 64; o <<= 1) { u32 v = __shfl_down(incl, o); if (lane + o < 64) incl += v; }
;   const u32 above = incl - c;
;   if ((int)above < need && need <= (int)incl) {
; DI void idx_job(const Params& p, int b, int qg, unsigned char* smem) {
;     ...
;   for (int qq = 0; qq < 4; ++qq) idx_scan(hist + (wave * 4 + qq) * 512, (int)needB[wave * 4 + qq], binB, needC, wave * 4 + qq, lane);
.LBB0_641:
	s_or_b64 exec, exec, s[2:3]
	s_waitcnt lgkmcnt(0)
	s_barrier
	s_waitcnt vmcnt(0)
	v_lshl_add_u32 v46, v109, 13, v96
	v_and_b32_e32 v48, 63, v207
	v_lshl_add_u32 v47, v109, 4, v96
	v_lshl_add_u32 v46, v48, 5, v46
	v_add_u32_e32 v47, 0xc000, v47
	ds_read_b128 v[168:171], v46
	ds_read_b128 v[172:175], v46 offset:16
	ds_read_b128 v[176:179], v46 offset:2048
	ds_read_b128 v[180:183], v46 offset:2064
	ds_read_b128 v[184:187], v46 offset:4096
	ds_read_b128 v[188:191], v46 offset:4112
	ds_read_b128 v[226:229], v46 offset:6144
	ds_read_b128 v[230:233], v46 offset:6160
	ds_read_b128 v[238:241], v47 offset:384
	s_waitcnt lgkmcnt(0)
	v_add3_u32 v192, v168, v169, v170
	v_add3_u32 v193, v176, v177, v178
	v_add3_u32 v194, v184, v185, v186
	v_add3_u32 v195, v226, v227, v228
	v_add3_u32 v192, v192, v171, v172
	v_add3_u32 v193, v193, v179, v180
	v_add3_u32 v194, v194, v187, v188
	v_add3_u32 v195, v195, v229, v230
	v_add3_u32 v192, v192, v173, v174
	v_add3_u32 v193, v193, v181, v182
	v_add3_u32 v194, v194, v189, v190
	v_add3_u32 v195, v195, v231, v232
	v_add_u32_e32 v192, v192, v175
	v_add_u32_e32 v193, v193, v183
	v_add_u32_e32 v194, v194, v191
	v_add_u32_e32 v195, v195, v233
	v_add_u32_sdwa v192, v192, v192 dst_sel:DWORD dst_unused:UNUSED_PAD src0_sel:WORD_0 src1_sel:WORD_1
	v_add_u32_sdwa v193, v193, v193 dst_sel:DWORD dst_unused:UNUSED_PAD src0_sel:WORD_0 src1_sel:WORD_1
	v_add_u32_sdwa v194, v194, v194 dst_sel:DWORD dst_unused:UNUSED_PAD src0_sel:WORD_0 src1_sel:WORD_1
	v_add_u32_sdwa v195, v195, v195 dst_sel:DWORD dst_unused:UNUSED_PAD src0_sel:WORD_0 src1_sel:WORD_1
	v_mov_b32_e32 v234, v192
	v_mov_b32_e32 v235, v193
	v_mov_b32_e32 v236, v194
	v_mov_b32_e32 v237, v195
	v_add_u32_dpp v234, v234, v234 row_shl:1 row_mask:0xf bank_mask:0xf
	v_add_u32_dpp v235, v235, v235 row_shl:1 row_mask:0xf bank_mask:0xf
	v_add_u32_dpp v236, v236, v236 row_shl:1 row_mask:0xf bank_mask:0xf
	v_add_u32_dpp v237, v237, v237 row_shl:1 row_mask:0xf bank_mask:0xf
	v_add_u32_dpp v234, v234, v234 row_shl:2 row_mask:0xf bank_mask:0xf
	v_add_u32_dpp v235, v235, v235 row_shl:2 row_mask:0xf bank_mask:0xf
	v_add_u32_dpp v236, v236, v236 row_shl:2 row_mask:0xf bank_mask:0xf
	v_add_u32_dpp v237, v237, v237 row_shl:2 row_mask:0xf bank_mask:0xf
	v_add_u32_dpp v234, v234, v234 row_shl:4 row_mask:0xf bank_mask:0xf
	v_add_u32_dpp v235, v235, v235 row_shl:4 row_mask:0xf bank_mask:0xf
	v_add_u32_dpp v236, v236, v236 row_shl:4 row_mask:0xf bank_mask:0xf
	v_add_u32_dpp v237, v237, v237 row_shl:4 row_mask:0xf bank_mask:0xf
	v_add_u32_dpp v234, v234, v234 row_shl:8 row_mask:0xf bank_mask:0xf
	v_add_u32_dpp v235, v235, v235 row_shl:8 row_mask:0xf bank_mask:0xf
	v_add_u32_dpp v236, v236, v236 row_shl:8 row_mask:0xf bank_mask:0xf
	v_add_u32_dpp v237, v237, v237 row_shl:8 row_mask:0xf bank_mask:0xf
	s_nop 1
	v_readlane_b32 s40, v234, 16
	v_readlane_b32 s41, v234, 32
	v_readlane_b32 s42, v234, 48
	v_readlane_b32 s43, v235, 16
	v_readlane_b32 s44, v235, 32
	v_readlane_b32 s45, v235, 48
	v_readlane_b32 s46, v236, 16
	v_readlane_b32 s47, v236, 32
	v_readlane_b32 s48, v236, 48
	v_readlane_b32 s49, v237, 16
	v_readlane_b32 s50, v237, 32
	v_readlane_b32 s51, v237, 48
	s_nop 0
	s_add_i32 s41, s41, s42
	s_add_i32 s40, s40, s41
	s_add_i32 s44, s44, s45
	s_add_i32 s43, s43, s44
	s_add_i32 s47, s47, s48
	s_add_i32 s46, s46, s47
	s_add_i32 s50, s50, s51
	s_add_i32 s49, s49, s50
	s_mov_b32 exec_lo, 0xffff
	s_mov_b32 exec_hi, 0
	v_add_u32_e32 v234, s40, v234
	v_add_u32_e32 v235, s43, v235
	v_add_u32_e32 v236, s46, v236
	v_add_u32_e32 v237, s49, v237
	s_mov_b32 exec_lo, 0xffff0000
	v_add_u32_e32 v234, s41, v234
	v_add_u32_e32 v235, s44, v235
	v_add_u32_e32 v236, s47, v236
	v_add_u32_e32 v237, s50, v237
	s_mov_b32 exec_lo, 0
	s_mov_b32 exec_hi, 0xffff
	v_add_u32_e32 v234, s42, v234
	v_add_u32_e32 v235, s45, v235
	v_add_u32_e32 v236, s48, v236
	v_add_u32_e32 v237, s51, v237
	s_mov_b64 exec, -1
	v_sub_u32_e32 v158, v234, v192
	v_sub_u32_e32 v159, v235, v193
	v_sub_u32_e32 v160, v236, v194
	v_sub_u32_e32 v161, v237, v195
	v_cmp_lt_u32_e64 s[4:5], v158, v238
	v_cmp_lt_u32_e64 s[6:7], v159, v239
	v_cmp_lt_u32_e64 s[8:9], v160, v240
	v_cmp_lt_u32_e64 s[28:29], v161, v241
	v_cmp_le_u32_e64 s[40:41], v238, v234
	v_cmp_le_u32_e64 s[42:43], v239, v235
	v_cmp_le_u32_e64 s[44:45], v240, v236
	v_cmp_le_u32_e64 s[46:47], v241, v237
	v_mov_b32_e32 v42, v158
	v_mov_b32_e32 v43, v159
	v_mov_b32_e32 v44, v160
	v_mov_b32_e32 v45, v161
	v_mov_b32_e32 v162, 15
	v_mov_b32_e32 v163, 15
	v_mov_b32_e32 v164, 15
	v_mov_b32_e32 v165, 15
	s_and_b64 s[40:41], s[40:41], s[4:5]
	s_and_b64 s[42:43], s[42:43], s[6:7]
	s_and_b64 s[44:45], s[44:45], s[8:9]
	s_and_b64 s[46:47], s[46:47], s[28:29]
	v_add_u32_sdwa v158, v175, v158 dst_sel:DWORD dst_unused:UNUSED_PAD src0_sel:WORD_1 src1_sel:DWORD
	v_add_u32_sdwa v159, v183, v159 dst_sel:DWORD dst_unused:UNUSED_PAD src0_sel:WORD_1 src1_sel:DWORD
	v_add_u32_sdwa v160, v191, v160 dst_sel:DWORD dst_unused:UNUSED_PAD src0_sel:WORD_1 src1_sel:DWORD
	v_add_u32_sdwa v161, v233, v161 dst_sel:DWORD dst_unused:UNUSED_PAD src0_sel:WORD_1 src1_sel:DWORD
	v_cmp_lt_u32_e64 s[4:5], v158, v238
	v_cmp_lt_u32_e64 s[6:7], v159, v239
	v_cmp_lt_u32_e64 s[8:9], v160, v240
	v_cmp_lt_u32_e64 s[28:29], v161, v241
	v_cndmask_b32_e64 v42, v42, v158, s[4:5]
	v_cndmask_b32_e64 v162, v162, 14, s[4:5]
	v_cndmask_b32_e64 v43, v43, v159, s[6:7]
	v_cndmask_b32_e64 v163, v163, 14, s[6:7]
	v_cndmask_b32_e64 v44, v44, v160, s[8:9]
	v_cndmask_b32_e64 v164, v164, 14, s[8:9]
	v_cndmask_b32_e64 v45, v45, v161, s[28:29]
	v_cndmask_b32_e64 v165, v165, 14, s[28:29]
	v_add_u32_sdwa v158, v175, v158 dst_sel:DWORD dst_unused:UNUSED_PAD src0_sel:WORD_0 src1_sel:DWORD
; DI void idx_scan(const u32* hq, int need, u32* outbin, u32* outneed, int q, int lane) {
;     ...
;   if ((int)above < need && need <= (int)incl) {
;     u32 cum = above;
;     ...
;       u32 cnt = (hq[bin >> 1] >> ((bin & 1) * 16)) & 0xffffu;
;       if ((int)(cum + cnt) >= need) { outbin[q] = (u32)bin; outneed[q] = (u32)need - cum; break; }
;       cum += cnt;
;     }
	v_add_u32_sdwa v159, v183, v159 dst_sel:DWORD dst_unused:UNUSED_PAD src0_sel:WORD_0 src1_sel:DWORD
	v_add_u32_sdwa v160, v191, v160 dst_sel:DWORD dst_unused:UNUSED_PAD src0_sel:WORD_0 src1_sel:DWORD
	v_add_u32_sdwa v161, v233, v161 dst_sel:DWORD dst_unused:UNUSED_PAD src0_sel:WORD_0 src1_sel:DWORD
	v_cmp_lt_u32_e64 s[4:5], v158, v238
	v_cmp_lt_u32_e64 s[6:7], v159, v239
	v_cmp_lt_u32_e64 s[8:9], v160, v240
	v_cmp_lt_u32_e64 s[28:29], v161, v241
	v_cndmask_b32_e64 v42, v42, v158, s[4:5]
	v_cndmask_b32_e64 v162, v162, 13, s[4:5]
	v_cndmask_b32_e64 v43, v43, v159, s[6:7]
	v_cndmask_b32_e64 v163, v163, 13, s[6:7]
	v_cndmask_b32_e64 v44, v44, v160, s[8:9]
	v_cndmask_b32_e64 v164, v164, 13, s[8:9]
	v_cndmask_b32_e64 v45, v45, v161, s[28:29]
	v_cndmask_b32_e64 v165, v165, 13, s[28:29]
	v_add_u32_sdwa v158, v174, v158 dst_sel:DWORD dst_unused:UNUSED_PAD src0_sel:WORD_1 src1_sel:DWORD
	v_add_u32_sdwa v159, v182, v159 dst_sel:DWORD dst_unused:UNUSED_PAD src0_sel:WORD_1 src1_sel:DWORD
	v_add_u32_sdwa v160, v190, v160 dst_sel:DWORD dst_unused:UNUSED_PAD src0_sel:WORD_1 src1_sel:DWORD
	v_add_u32_sdwa v161, v232, v161 dst_sel:DWORD dst_unused:UNUSED_PAD src0_sel:WORD_1 src1_sel:DWORD
	v_cmp_lt_u32_e64 s[4:5], v158, v238
	v_cmp_lt_u32_e64 s[6:7], v159, v239
	v_cmp_lt_u32_e64 s[8:9], v160, v240
	v_cmp_lt_u32_e64 s[28:29], v161, v241
	v_cndmask_b32_e64 v42, v42, v158, s[4:5]
	v_cndmask_b32_e64 v162, v162, 12, s[4:5]
	v_cndmask_b32_e64 v43, v43, v159, s[6:7]
	v_cndmask_b32_e64 v163, v163, 12, s[6:7]
	v_cndmask_b32_e64 v44, v44, v160, s[8:9]
	v_cndmask_b32_e64 v164, v164, 12, s[8:9]
	v_cndmask_b32_e64 v45, v45, v161, s[28:29]
	v_cndmask_b32_e64 v165, v165, 12, s[28:29]
	v_add_u32_sdwa v158, v174, v158 dst_sel:DWORD dst_unused:UNUSED_PAD src0_sel:WORD_0 src1_sel:DWORD
	v_add_u32_sdwa v159, v182, v159 dst_sel:DWORD dst_unused:UNUSED_PAD src0_sel:WORD_0 src1_sel:DWORD
	v_add_u32_sdwa v160, v190, v160 dst_sel:DWORD dst_unused:UNUSED_PAD src0_sel:WORD_0 src1_sel:DWORD
	v_add_u32_sdwa v161, v232, v161 dst_sel:DWORD dst_unused:UNUSED_PAD src0_sel:WORD_0 src1_sel:DWORD
	v_cmp_lt_u32_e64 s[4:5], v158, v238
	v_cmp_lt_u32_e64 s[6:7], v159, v239
	v_cmp_lt_u32_e64 s[8:9], v160, v240
	v_cmp_lt_u32_e64 s[28:29], v161, v241
	v_cndmask_b32_e64 v42, v42, v158, s[4:5]
	v_cndmask_b32_e64 v162, v162, 11, s[4:5]
	v_cndmask_b32_e64 v43, v43, v159, s[6:7]
	v_cndmask_b32_e64 v163, v163, 11, s[6:7]
	v_cndmask_b32_e64 v44, v44, v160, s[8:9]
	v_cndmask_b32_e64 v164, v164, 11, s[8:9]
	v_cndmask_b32_e64 v45, v45, v161, s[28:29]
	v_cndmask_b32_e64 v165, v165, 11, s[28:29]
	v_add_u32_sdwa v158, v173, v158 dst_sel:DWORD dst_unused:UNUSED_PAD src0_sel:WORD_1 src1_sel:DWORD
	v_add_u32_sdwa v159, v181, v159 dst_sel:DWORD dst_unused:UNUSED_PAD src0_sel:WORD_1 src1_sel:DWORD
	v_add_u32_sdwa v160, v189, v160 dst_sel:DWORD dst_unused:UNUSED_PAD src0_sel:WORD_1 src1_sel:DWORD
	v_add_u32_sdwa v161, v231, v161 dst_sel:DWORD dst_unused:UNUSED_PAD src0_sel:WORD_1 src1_sel:DWORD
	v_cmp_lt_u32_e64 s[4:5], v158, v238
	v_cmp_lt_u32_e64 s[6:7], v159, v239
	v_cmp_lt_u32_e64 s[8:9], v160, v240
	v_cmp_lt_u32_e64 s[28:29], v161, v241
	v_cndmask_b32_e64 v42, v42, v158, s[4:5]
	v_cndmask_b32_e64 v162, v162, 10, s[4:5]
	v_cndmask_b32_e64 v43, v43, v159, s[6:7]
	v_cndmask_b32_e64 v163, v163, 10, s[6:7]
	v_cndmask_b32_e64 v44, v44, v160, s[8:9]
	v_cndmask_b32_e64 v164, v164, 10, s[8:9]
	v_cndmask_b32_e64 v45, v45, v161, s[28:29]
	v_cndmask_b32_e64 v165, v165, 10, s[28:29]
	v_add_u32_sdwa v158, v173, v158 dst_sel:DWORD dst_unused:UNUSED_PAD src0_sel:WORD_0 src1_sel:DWORD
	v_add_u32_sdwa v159, v181, v159 dst_sel:DWORD dst_unused:UNUSED_PAD src0_sel:WORD_0 src1_sel:DWORD
	v_add_u32_sdwa v160, v189, v160 dst_sel:DWORD dst_unused:UNUSED_PAD src0_sel:WORD_0 src1_sel:DWORD
	v_add_u32_sdwa v161, v231, v161 dst_sel:DWORD dst_unused:UNUSED_PAD src0_sel:WORD_0 src1_sel:DWORD
	v_cmp_lt_u32_e64 s[4:5], v158, v238
	v_cmp_lt_u32_e64 s[6:7], v159, v239
	v_cmp_lt_u32_e64 s[8:9], v160, v240
	v_cmp_lt_u32_e64 s[28:29], v161, v241
	v_cndmask_b32_e64 v42, v42, v158, s[4:5]
	v_cndmask_b32_e64 v162, v162, 9, s[4:5]
	v_cndmask_b32_e64 v43, v43, v159, s[6:7]
	v_cndmask_b32_e64 v163, v163, 9, s[6:7]
	v_cndmask_b32_e64 v44, v44, v160, s[8:9]
	v_cndmask_b32_e64 v164, v164, 9, s[8:9]
	v_cndmask_b32_e64 v45, v45, v161, s[28:29]
	v_cndmask_b32_e64 v165, v165, 9, s[28:29]
	v_add_u32_sdwa v158, v172, v158 dst_sel:DWORD dst_unused:UNUSED_PAD src0_sel:WORD_1 src1_sel:DWORD
	v_add_u32_sdwa v159, v180, v159 dst_sel:DWORD dst_unused:UNUSED_PAD src0_sel:WORD_1 src1_sel:DWORD
	v_add_u32_sdwa v160, v188, v160 dst_sel:DWORD dst_unused:UNUSED_PAD src0_sel:WORD_1 src1_sel:DWORD
	v_add_u32_sdwa v161, v230, v161 dst_sel:DWORD dst_unused:UNUSED_PAD src0_sel:WORD_1 src1_sel:DWORD
	v_cmp_lt_u32_e64 s[4:5], v158, v238
	v_cmp_lt_u32_e64 s[6:7], v159, v239
	v_cmp_lt_u32_e64 s[8:9], v160, v240
	v_cmp_lt_u32_e64 s[28:29], v161, v241
	v_cndmask_b32_e64 v42, v42, v158, s[4:5]
	v_cndmask_b32_e64 v162, v162, 8, s[4:5]
	v_cndmask_b32_e64 v43, v43, v159, s[6:7]
	v_cndmask_b32_e64 v163, v163, 8, s[6:7]
	v_cndmask_b32_e64 v44, v44, v160, s[8:9]
	v_cndmask_b32_e64 v164, v164, 8, s[8:9]
	v_cndmask_b32_e64 v45, v45, v161, s[28:29]
	v_cndmask_b32_e64 v165, v165, 8, s[28:29]
	v_add_u32_sdwa v158, v172, v158 dst_sel:DWORD dst_unused:UNUSED_PAD src0_sel:WORD_0 src1_sel:DWORD
	v_add_u32_sdwa v159, v180, v159 dst_sel:DWORD dst_unused:UNUSED_PAD src0_sel:WORD_0 src1_sel:DWORD
	v_add_u32_sdwa v160, v188, v160 dst_sel:DWORD dst_unused:UNUSED_PAD src0_sel:WORD_0 src1_sel:DWORD
	v_add_u32_sdwa v161, v230, v161 dst_sel:DWORD dst_unused:UNUSED_PAD src0_sel:WORD_0 src1_sel:DWORD
; DI void idx_scan(const u32* hq, int need, u32* outbin, u32* outneed, int q, int lane) {
;     ...
;   if ((int)above < need && need <= (int)incl) {
;     u32 cum = above;
;     ...
;       u32 cnt = (hq[bin >> 1] >> ((bin & 1) * 16)) & 0xffffu;
;       if ((int)(cum + cnt) >= need) { outbin[q] = (u32)bin; outneed[q] = (u32)need - cum; break; }
;       cum += cnt;
;     }
	v_cmp_lt_u32_e64 s[4:5], v158, v238
	v_cmp_lt_u32_e64 s[6:7], v159, v239
	v_cmp_lt_u32_e64 s[8:9], v160, v240
	v_cmp_lt_u32_e64 s[28:29], v161, v241
	v_cndmask_b32_e64 v42, v42, v158, s[4:5]
	v_cndmask_b32_e64 v162, v162, 7, s[4:5]
	v_cndmask_b32_e64 v43, v43, v159, s[6:7]
	v_cndmask_b32_e64 v163, v163, 7, s[6:7]
	v_cndmask_b32_e64 v44, v44, v160, s[8:9]
	v_cndmask_b32_e64 v164, v164, 7, s[8:9]
	v_cndmask_b32_e64 v45, v45, v161, s[28:29]
	v_cndmask_b32_e64 v165, v165, 7, s[28:29]
	v_add_u32_sdwa v158, v171, v158 dst_sel:DWORD dst_unused:UNUSED_PAD src0_sel:WORD_1 src1_sel:DWORD
	v_add_u32_sdwa v159, v179, v159 dst_sel:DWORD dst_unused:UNUSED_PAD src0_sel:WORD_1 src1_sel:DWORD
	v_add_u32_sdwa v160, v187, v160 dst_sel:DWORD dst_unused:UNUSED_PAD src0_sel:WORD_1 src1_sel:DWORD
	v_add_u32_sdwa v161, v229, v161 dst_sel:DWORD dst_unused:UNUSED_PAD src0_sel:WORD_1 src1_sel:DWORD
	v_cmp_lt_u32_e64 s[4:5], v158, v238
	v_cmp_lt_u32_e64 s[6:7], v159, v239
	v_cmp_lt_u32_e64 s[8:9], v160, v240
	v_cmp_lt_u32_e64 s[28:29], v161, v241
	v_cndmask_b32_e64 v42, v42, v158, s[4:5]
	v_cndmask_b32_e64 v162, v162, 6, s[4:5]
	v_cndmask_b32_e64 v43, v43, v159, s[6:7]
	v_cndmask_b32_e64 v163, v163, 6, s[6:7]
	v_cndmask_b32_e64 v44, v44, v160, s[8:9]
	v_cndmask_b32_e64 v164, v164, 6, s[8:9]
	v_cndmask_b32_e64 v45, v45, v161, s[28:29]
	v_cndmask_b32_e64 v165, v165, 6, s[28:29]
	v_add_u32_sdwa v158, v171, v158 dst_sel:DWORD dst_unused:UNUSED_PAD src0_sel:WORD_0 src1_sel:DWORD
	v_add_u32_sdwa v159, v179, v159 dst_sel:DWORD dst_unused:UNUSED_PAD src0_sel:WORD_0 src1_sel:DWORD
	v_add_u32_sdwa v160, v187, v160 dst_sel:DWORD dst_unused:UNUSED_PAD src0_sel:WORD_0 src1_sel:DWORD
	v_add_u32_sdwa v161, v229, v161 dst_sel:DWORD dst_unused:UNUSED_PAD src0_sel:WORD_0 src1_sel:DWORD
	v_cmp_lt_u32_e64 s[4:5], v158, v238
	v_cmp_lt_u32_e64 s[6:7], v159, v239
	v_cmp_lt_u32_e64 s[8:9], v160, v240
	v_cmp_lt_u32_e64 s[28:29], v161, v241
	v_cndmask_b32_e64 v42, v42, v158, s[4:5]
	v_cndmask_b32_e64 v162, v162, 5, s[4:5]
	v_cndmask_b32_e64 v43, v43, v159, s[6:7]
	v_cndmask_b32_e64 v163, v163, 5, s[6:7]
	v_cndmask_b32_e64 v44, v44, v160, s[8:9]
	v_cndmask_b32_e64 v164, v164, 5, s[8:9]
	v_cndmask_b32_e64 v45, v45, v161, s[28:29]
	v_cndmask_b32_e64 v165, v165, 5, s[28:29]
	v_add_u32_sdwa v158, v170, v158 dst_sel:DWORD dst_unused:UNUSED_PAD src0_sel:WORD_1 src1_sel:DWORD
	v_add_u32_sdwa v159, v178, v159 dst_sel:DWORD dst_unused:UNUSED_PAD src0_sel:WORD_1 src1_sel:DWORD
	v_add_u32_sdwa v160, v186, v160 dst_sel:DWORD dst_unused:UNUSED_PAD src0_sel:WORD_1 src1_sel:DWORD
	v_add_u32_sdwa v161, v228, v161 dst_sel:DWORD dst_unused:UNUSED_PAD src0_sel:WORD_1 src1_sel:DWORD
	v_cmp_lt_u32_e64 s[4:5], v158, v238
	v_cmp_lt_u32_e64 s[6:7], v159, v239
	v_cmp_lt_u32_e64 s[8:9], v160, v240
	v_cmp_lt_u32_e64 s[28:29], v161, v241
	v_cndmask_b32_e64 v42, v42, v158, s[4:5]
	v_cndmask_b32_e64 v162, v162, 4, s[4:5]
	v_cndmask_b32_e64 v43, v43, v159, s[6:7]
	v_cndmask_b32_e64 v163, v163, 4, s[6:7]
	v_cndmask_b32_e64 v44, v44, v160, s[8:9]
	v_cndmask_b32_e64 v164, v164, 4, s[8:9]
	v_cndmask_b32_e64 v45, v45, v161, s[28:29]
	v_cndmask_b32_e64 v165, v165, 4, s[28:29]
	v_add_u32_sdwa v158, v170, v158 dst_sel:DWORD dst_unused:UNUSED_PAD src0_sel:WORD_0 src1_sel:DWORD
	v_add_u32_sdwa v159, v178, v159 dst_sel:DWORD dst_unused:UNUSED_PAD src0_sel:WORD_0 src1_sel:DWORD
	v_add_u32_sdwa v160, v186, v160 dst_sel:DWORD dst_unused:UNUSED_PAD src0_sel:WORD_0 src1_sel:DWORD
	v_add_u32_sdwa v161, v228, v161 dst_sel:DWORD dst_unused:UNUSED_PAD src0_sel:WORD_0 src1_sel:DWORD
	v_cmp_lt_u32_e64 s[4:5], v158, v238
	v_cmp_lt_u32_e64 s[6:7], v159, v239
	v_cmp_lt_u32_e64 s[8:9], v160, v240
	v_cmp_lt_u32_e64 s[28:29], v161, v241
	v_cndmask_b32_e64 v42, v42, v158, s[4:5]
	v_cndmask_b32_e64 v162, v162, 3, s[4:5]
	v_cndmask_b32_e64 v43, v43, v159, s[6:7]
	v_cndmask_b32_e64 v163, v163, 3, s[6:7]
	v_cndmask_b32_e64 v44, v44, v160, s[8:9]
	v_cndmask_b32_e64 v164, v164, 3, s[8:9]
	v_cndmask_b32_e64 v45, v45, v161, s[28:29]
	v_cndmask_b32_e64 v165, v165, 3, s[28:29]
	v_add_u32_sdwa v158, v169, v158 dst_sel:DWORD dst_unused:UNUSED_PAD src0_sel:WORD_1 src1_sel:DWORD
	v_add_u32_sdwa v159, v177, v159 dst_sel:DWORD dst_unused:UNUSED_PAD src0_sel:WORD_1 src1_sel:DWORD
	v_add_u32_sdwa v160, v185, v160 dst_sel:DWORD dst_unused:UNUSED_PAD src0_sel:WORD_1 src1_sel:DWORD
	v_add_u32_sdwa v161, v227, v161 dst_sel:DWORD dst_unused:UNUSED_PAD src0_sel:WORD_1 src1_sel:DWORD
	v_cmp_lt_u32_e64 s[4:5], v158, v238
	v_cmp_lt_u32_e64 s[6:7], v159, v239
	v_cmp_lt_u32_e64 s[8:9], v160, v240
	v_cmp_lt_u32_e64 s[28:29], v161, v241
	v_cndmask_b32_e64 v42, v42, v158, s[4:5]
	v_cndmask_b32_e64 v162, v162, 2, s[4:5]
; DI void idx_scan(const u32* hq, int need, u32* outbin, u32* outneed, int q, int lane) {
;     ...
;       u32 cnt = (hq[bin >> 1] >> ((bin & 1) * 16)) & 0xffffu;
;       if ((int)(cum + cnt) >= need) { outbin[q] = (u32)bin; outneed[q] = (u32)need - cum; break; }
;       cum += cnt;
;     }
;   }
; template <int PASS>
; DI void idx_pass(const u16* kp, const bf16x8 (&qf)[8], const float (&wq)[8], int wave, int ntile, int lm, int lg, int tq, bool selall,
;                  u32 bA, u32 pfx, u32* hist, u32* maskw, u32* cand, u32* ccnt) {
;   auto ldk = [&](int t) { return *(const bf16x8*)(kp + (size_t)(t < ntile ? t : 0) * 512); };
;   int kt = wave;
;   bf16x8 ka = ldk(kt), kb = ldk(kt + 4);
	v_cndmask_b32_e64 v43, v43, v159, s[6:7]
	v_cndmask_b32_e64 v163, v163, 2, s[6:7]
	v_cndmask_b32_e64 v44, v44, v160, s[8:9]
	v_cndmask_b32_e64 v164, v164, 2, s[8:9]
	v_cndmask_b32_e64 v45, v45, v161, s[28:29]
	v_cndmask_b32_e64 v165, v165, 2, s[28:29]
	v_add_u32_sdwa v158, v169, v158 dst_sel:DWORD dst_unused:UNUSED_PAD src0_sel:WORD_0 src1_sel:DWORD
	v_add_u32_sdwa v159, v177, v159 dst_sel:DWORD dst_unused:UNUSED_PAD src0_sel:WORD_0 src1_sel:DWORD
	v_add_u32_sdwa v160, v185, v160 dst_sel:DWORD dst_unused:UNUSED_PAD src0_sel:WORD_0 src1_sel:DWORD
	v_add_u32_sdwa v161, v227, v161 dst_sel:DWORD dst_unused:UNUSED_PAD src0_sel:WORD_0 src1_sel:DWORD
	v_cmp_lt_u32_e64 s[4:5], v158, v238
	v_cmp_lt_u32_e64 s[6:7], v159, v239
	v_cmp_lt_u32_e64 s[8:9], v160, v240
	v_cmp_lt_u32_e64 s[28:29], v161, v241
	v_cndmask_b32_e64 v42, v42, v158, s[4:5]
	v_cndmask_b32_e64 v162, v162, 1, s[4:5]
	v_cndmask_b32_e64 v43, v43, v159, s[6:7]
	v_cndmask_b32_e64 v163, v163, 1, s[6:7]
	v_cndmask_b32_e64 v44, v44, v160, s[8:9]
	v_cndmask_b32_e64 v164, v164, 1, s[8:9]
	v_cndmask_b32_e64 v45, v45, v161, s[28:29]
	v_cndmask_b32_e64 v165, v165, 1, s[28:29]
	v_add_u32_sdwa v158, v168, v158 dst_sel:DWORD dst_unused:UNUSED_PAD src0_sel:WORD_1 src1_sel:DWORD
	v_add_u32_sdwa v159, v176, v159 dst_sel:DWORD dst_unused:UNUSED_PAD src0_sel:WORD_1 src1_sel:DWORD
	v_add_u32_sdwa v160, v184, v160 dst_sel:DWORD dst_unused:UNUSED_PAD src0_sel:WORD_1 src1_sel:DWORD
	v_add_u32_sdwa v161, v226, v161 dst_sel:DWORD dst_unused:UNUSED_PAD src0_sel:WORD_1 src1_sel:DWORD
	v_cmp_lt_u32_e64 s[4:5], v158, v238
	v_cmp_lt_u32_e64 s[6:7], v159, v239
	v_cmp_lt_u32_e64 s[8:9], v160, v240
	v_cmp_lt_u32_e64 s[28:29], v161, v241
	v_cndmask_b32_e64 v42, v42, v158, s[4:5]
	v_cndmask_b32_e64 v162, v162, 0, s[4:5]
	v_cndmask_b32_e64 v43, v43, v159, s[6:7]
	v_cndmask_b32_e64 v163, v163, 0, s[6:7]
	v_cndmask_b32_e64 v44, v44, v160, s[8:9]
	v_cndmask_b32_e64 v164, v164, 0, s[8:9]
	v_cndmask_b32_e64 v45, v45, v161, s[28:29]
	v_cndmask_b32_e64 v165, v165, 0, s[28:29]
	v_add_u32_sdwa v158, v168, v158 dst_sel:DWORD dst_unused:UNUSED_PAD src0_sel:WORD_0 src1_sel:DWORD
	v_add_u32_sdwa v159, v176, v159 dst_sel:DWORD dst_unused:UNUSED_PAD src0_sel:WORD_0 src1_sel:DWORD
	v_add_u32_sdwa v160, v184, v160 dst_sel:DWORD dst_unused:UNUSED_PAD src0_sel:WORD_0 src1_sel:DWORD
	v_add_u32_sdwa v161, v226, v161 dst_sel:DWORD dst_unused:UNUSED_PAD src0_sel:WORD_0 src1_sel:DWORD
	v_cmp_lt_u32_e64 s[4:5], v158, v238
	v_cmp_lt_u32_e64 s[6:7], v159, v239
	v_cmp_lt_u32_e64 s[8:9], v160, v240
	v_cmp_lt_u32_e64 s[28:29], v161, v241
	v_cndmask_b32_e64 v42, v42, v158, s[4:5]
	v_cndmask_b32_e64 v162, v162, -1, s[4:5]
	v_cndmask_b32_e64 v43, v43, v159, s[6:7]
	v_cndmask_b32_e64 v163, v163, -1, s[6:7]
	v_cndmask_b32_e64 v44, v44, v160, s[8:9]
	v_cndmask_b32_e64 v164, v164, -1, s[8:9]
	v_cndmask_b32_e64 v45, v45, v161, s[28:29]
	v_cndmask_b32_e64 v165, v165, -1, s[28:29]
	v_lshl_add_u32 v50, v48, 4, v162
	v_lshl_add_u32 v51, v48, 4, v163
	v_lshl_add_u32 v52, v48, 4, v164
	v_lshl_add_u32 v53, v48, 4, v165
	v_sub_u32_e32 v54, v238, v42
	v_sub_u32_e32 v55, v239, v43
	v_sub_u32_e32 v242, v240, v44
	v_sub_u32_e32 v243, v241, v45
	s_mov_b64 exec, s[40:41]
	ds_write2_b32 v47, v50, v54 offset0:112 offset1:128
	s_mov_b64 exec, s[42:43]
	ds_write2_b32 v47, v51, v55 offset0:113 offset1:129
	s_mov_b64 exec, s[44:45]
	ds_write2_b32 v47, v52, v242 offset0:114 offset1:130
	s_mov_b64 exec, s[46:47]
	ds_write2_b32 v47, v53, v243 offset0:115 offset1:131
	s_mov_b64 exec, -1
	s_waitcnt lgkmcnt(0)
	s_barrier
	s_cbranch_vccz .Lidx2_nl
	v_sub_u32_e32 v160, v97, v109
	v_subrev_u32_e32 v160, 5, v160
	v_and_b32_e32 v160, -8, v160
	v_add_u32_e32 v160, v160, v109
	v_add_u32_e32 v162, 12, v160
	v_add_u32_e32 v160, 8, v160
	v_cmp_le_i32_e64 s[4:5], v160, v97
	v_cmp_le_i32_e64 s[8:9], v162, v97
	v_mov_b32_e32 v161, 0
	v_mov_b32_e32 v163, 0
	v_cndmask_b32_e64 v160, 0, v160, s[4:5]
	v_cndmask_b32_e64 v162, 0, v162, s[8:9]
	v_lshlrev_b64 v[160:161], 10, v[160:161]
	v_lshlrev_b64 v[162:163], 10, v[162:163]
	v_lshl_add_u64 v[160:161], v[90:91], 0, v[160:161]
	v_lshl_add_u64 v[162:163], v[90:91], 0, v[162:163]
	global_load_dwordx4 v[192:195], v[160:161], off
	global_load_dwordx4 v[226:229], v[162:163], off
	v_lshl_add_u32 v182, v109, 10, v250
	s_add_u32 s92, s90, 0x1000
	s_addc_u32 s93, s91, 0
	v_readfirstlane_b32 s88, v109
	v_readfirstlane_b32 s89, v97
	global_load_dwordx4 v[184:187], v182, s[90:91]
	global_load_dwordx4 v[188:191], v182, s[92:93]
	v_add_u32_e32 v183, 0x2000, v182
	global_load_dwordx4 v[230:233], v183, s[90:91]
	global_load_dwordx4 v[234:237], v183, s[92:93]
	v_add_u32_e32 v182, 0x4000, v182
	s_branch .Lidx2_pj
